# stack3 + gate/up GEMM SwiGLU epilogue re-emitted as eight interleaved element chains (same operations and order per element)
# speedup vs baseline: 1.0257x; 1.0050x over previous
; __device__ __forceinline__ unsigned cvt_pk_bf16(float lo, float hi) { unsigned r; asm volatile("v_cvt_pk_bf16_f32 %0, %1, %2" : "=v"(r) : "v"(lo), "v"(hi)); return r; }
;     __device__ __forceinline__ void operator()(const f32x4 (&acc)[2][2][4][2], const Unit& u, int wr, int wc, int fr, int fq, const float (&rsv)[8]) const {
;         const int row0 = u.pm * BM + wr * 64 + fr, col0 = u.pn * HALF + wc * 32 + 8 * fq;
; #pragma unroll
;         for (int ai = 0; ai < 2; ++ai)
; #pragma unroll
;             for (int m = 0; m < 4; ++m) { bf16_t* rowp = O + (size_t)(row0 + ai * HALF + m * 16) * ldc + col0; float r[8]; const float rr = rsv[ai * 4 + m];
; #pragma unroll
;                 for (int n = 0; n < 2; ++n)
; #pragma unroll
;                     for (int j = 0; j < 4; ++j) { const float g = acc[ai][0][m][n][j] * rr, up = acc[ai][1][m][n][j] * rr;
;                         const float e = __builtin_amdgcn_exp2f(g * -1.4426950408889634f); r[n * 4 + j] = g * __builtin_amdgcn_rcpf(1.0f + e) * up; }
;                 u32x4 w; w.x = cvt_pk_bf16(r[0], r[1]); w.y = cvt_pk_bf16(r[2], r[3]); w.z = cvt_pk_bf16(r[4], r[5]); w.w = cvt_pk_bf16(r[6], r[7]);
;                 *(u32x4*)rowp = w; }
.LBB0_625:
	s_waitcnt vmcnt(8)
	v_lshl_or_b32 v160, s42, 7, v147
	v_ashrrev_i32_e32 v161, 31, v160
	v_mov_b64_e32 v[154:155], s[12:13]
	v_lshlrev_b64 v[164:165], 1, v[160:161]
	v_mad_i64_i32 v[162:163], s[42:43], v142, s65, v[154:155]
	v_mul_f32_e32 v126, v158, v126
	v_mul_f32_e32 v127, v158, v127
	v_mul_f32_e32 v128, v158, v128
	v_mul_f32_e32 v129, v158, v129
	v_mul_f32_e32 v118, v158, v118
	v_mul_f32_e32 v119, v158, v119
	v_mul_f32_e32 v120, v158, v120
	v_mul_f32_e32 v121, v158, v121
	v_mul_f32_e32 v122, v158, v122
	v_mul_f32_e32 v123, v158, v123
	v_mul_f32_e32 v124, v158, v124
	v_mul_f32_e32 v125, v158, v125
	v_mul_f32_e32 v114, v158, v114
	v_mul_f32_e32 v115, v158, v115
	v_mul_f32_e32 v116, v158, v116
	v_mul_f32_e32 v117, v158, v117
	v_mul_f32_e32 v168, 0xbfb8aa3b, v126
	v_mul_f32_e32 v169, 0xbfb8aa3b, v127
	v_mul_f32_e32 v170, 0xbfb8aa3b, v128
	v_mul_f32_e32 v171, 0xbfb8aa3b, v129
	v_mul_f32_e32 v172, 0xbfb8aa3b, v118
	v_mul_f32_e32 v173, 0xbfb8aa3b, v119
	v_mul_f32_e32 v174, 0xbfb8aa3b, v120
	v_mul_f32_e32 v175, 0xbfb8aa3b, v121
	v_exp_f32_e32 v168, v168
	v_exp_f32_e32 v169, v169
	v_exp_f32_e32 v170, v170
	v_exp_f32_e32 v171, v171
	v_exp_f32_e32 v172, v172
	v_exp_f32_e32 v173, v173
	v_exp_f32_e32 v174, v174
	v_exp_f32_e32 v175, v175
	v_add_f32_e32 v168, 1.0, v168
	v_add_f32_e32 v169, 1.0, v169
	v_add_f32_e32 v170, 1.0, v170
	v_add_f32_e32 v171, 1.0, v171
	v_add_f32_e32 v172, 1.0, v172
	v_add_f32_e32 v173, 1.0, v173
	v_add_f32_e32 v174, 1.0, v174
	v_add_f32_e32 v175, 1.0, v175
	v_rcp_f32_e32 v168, v168
	v_rcp_f32_e32 v169, v169
	v_rcp_f32_e32 v170, v170
	v_rcp_f32_e32 v171, v171
	v_rcp_f32_e32 v172, v172
	v_rcp_f32_e32 v173, v173
	v_rcp_f32_e32 v174, v174
	v_rcp_f32_e32 v175, v175
	v_mul_f32_e32 v126, v126, v168
	v_mul_f32_e32 v127, v127, v169
	v_mul_f32_e32 v128, v128, v170
	v_mul_f32_e32 v129, v129, v171
	v_mul_f32_e32 v118, v118, v172
	v_mul_f32_e32 v119, v119, v173
	v_mul_f32_e32 v120, v120, v174
	v_mul_f32_e32 v121, v121, v175
	v_mul_f32_e32 v126, v126, v122
	v_mul_f32_e32 v127, v127, v123
	v_mul_f32_e32 v128, v128, v124
	v_mul_f32_e32 v129, v129, v125
	v_mul_f32_e32 v118, v118, v114
	v_mul_f32_e32 v119, v119, v115
	v_mul_f32_e32 v120, v120, v116
	v_mul_f32_e32 v121, v121, v117
	v_lshl_add_u64 v[162:163], v[162:163], 0, v[164:165]
	v_cvt_pk_bf16_f32 v122, v126, v127
	v_cvt_pk_bf16_f32 v123, v128, v129
	v_cvt_pk_bf16_f32 v124, v118, v119
	v_cvt_pk_bf16_f32 v125, v120, v121
	global_store_dwordx4 v[162:163], v[122:125], off
	v_add_u32_e32 v176, 0x10, v142
	v_mad_i64_i32 v[166:167], s[42:43], v176, s65, v[154:155]
	v_mul_f32_e32 v110, v156, v110
	v_mul_f32_e32 v111, v156, v111
	v_mul_f32_e32 v112, v156, v112
	v_mul_f32_e32 v113, v156, v113
	v_mul_f32_e32 v102, v156, v102
	v_mul_f32_e32 v103, v156, v103
	v_mul_f32_e32 v104, v156, v104
	v_mul_f32_e32 v105, v156, v105
	v_mul_f32_e32 v106, v156, v106
	v_mul_f32_e32 v107, v156, v107
	v_mul_f32_e32 v108, v156, v108
	v_mul_f32_e32 v109, v156, v109
	v_mul_f32_e32 v98, v156, v98
	v_mul_f32_e32 v99, v156, v99
	v_mul_f32_e32 v100, v156, v100
	v_mul_f32_e32 v101, v156, v101
	v_mul_f32_e32 v168, 0xbfb8aa3b, v110
	v_mul_f32_e32 v169, 0xbfb8aa3b, v111
	v_mul_f32_e32 v170, 0xbfb8aa3b, v112
	v_mul_f32_e32 v171, 0xbfb8aa3b, v113
	v_mul_f32_e32 v172, 0xbfb8aa3b, v102
	v_mul_f32_e32 v173, 0xbfb8aa3b, v103
	v_mul_f32_e32 v174, 0xbfb8aa3b, v104
	v_mul_f32_e32 v175, 0xbfb8aa3b, v105
	v_exp_f32_e32 v168, v168
	v_exp_f32_e32 v169, v169
	v_exp_f32_e32 v170, v170
	v_exp_f32_e32 v171, v171
	v_exp_f32_e32 v172, v172
	v_exp_f32_e32 v173, v173
	v_exp_f32_e32 v174, v174
	v_exp_f32_e32 v175, v175
	v_add_f32_e32 v168, 1.0, v168
	v_add_f32_e32 v169, 1.0, v169
	v_add_f32_e32 v170, 1.0, v170
	v_add_f32_e32 v171, 1.0, v171
	v_add_f32_e32 v172, 1.0, v172
	v_add_f32_e32 v173, 1.0, v173
	v_add_f32_e32 v174, 1.0, v174
	v_add_f32_e32 v175, 1.0, v175
	v_rcp_f32_e32 v168, v168
	v_rcp_f32_e32 v169, v169
	v_rcp_f32_e32 v170, v170
	v_rcp_f32_e32 v171, v171
	v_rcp_f32_e32 v172, v172
	v_rcp_f32_e32 v173, v173
	v_rcp_f32_e32 v174, v174
	v_rcp_f32_e32 v175, v175
	v_mul_f32_e32 v110, v110, v168
	v_mul_f32_e32 v111, v111, v169
	v_mul_f32_e32 v112, v112, v170
	v_mul_f32_e32 v113, v113, v171
	v_mul_f32_e32 v102, v102, v172
	v_mul_f32_e32 v103, v103, v173
	v_mul_f32_e32 v104, v104, v174
	v_mul_f32_e32 v105, v105, v175
	v_mul_f32_e32 v110, v110, v106
	v_mul_f32_e32 v111, v111, v107
	v_mul_f32_e32 v112, v112, v108
	v_mul_f32_e32 v113, v113, v109
	v_mul_f32_e32 v102, v102, v98
	v_mul_f32_e32 v103, v103, v99
	v_mul_f32_e32 v104, v104, v100
	v_mul_f32_e32 v105, v105, v101
	v_lshl_add_u64 v[166:167], v[166:167], 0, v[164:165]
	v_cvt_pk_bf16_f32 v106, v110, v111
	v_cvt_pk_bf16_f32 v107, v112, v113
	v_cvt_pk_bf16_f32 v108, v102, v103
	v_cvt_pk_bf16_f32 v109, v104, v105
	global_store_dwordx4 v[166:167], v[106:109], off
	v_add_u32_e32 v176, 0x20, v142
	v_mad_i64_i32 v[162:163], s[42:43], v176, s65, v[154:155]
	v_mul_f32_e32 v94, v152, v94
	v_mul_f32_e32 v95, v152, v95
	v_mul_f32_e32 v96, v152, v96
	v_mul_f32_e32 v97, v152, v97
	v_mul_f32_e32 v86, v152, v86
	v_mul_f32_e32 v87, v152, v87
	v_mul_f32_e32 v88, v152, v88
	v_mul_f32_e32 v89, v152, v89
	v_mul_f32_e32 v90, v152, v90
	v_mul_f32_e32 v91, v152, v91
	v_mul_f32_e32 v92, v152, v92
	v_mul_f32_e32 v93, v152, v93
	v_mul_f32_e32 v82, v152, v82
	v_mul_f32_e32 v83, v152, v83
	v_mul_f32_e32 v84, v152, v84
	v_mul_f32_e32 v85, v152, v85
	v_mul_f32_e32 v168, 0xbfb8aa3b, v94
	v_mul_f32_e32 v169, 0xbfb8aa3b, v95
	v_mul_f32_e32 v170, 0xbfb8aa3b, v96
	v_mul_f32_e32 v171, 0xbfb8aa3b, v97
	v_mul_f32_e32 v172, 0xbfb8aa3b, v86
	v_mul_f32_e32 v173, 0xbfb8aa3b, v87
	v_mul_f32_e32 v174, 0xbfb8aa3b, v88
; __device__ __forceinline__ unsigned cvt_pk_bf16(float lo, float hi) { unsigned r; asm volatile("v_cvt_pk_bf16_f32 %0, %1, %2" : "=v"(r) : "v"(lo), "v"(hi)); return r; }
;     __device__ __forceinline__ void operator()(const f32x4 (&acc)[2][2][4][2], const Unit& u, int wr, int wc, int fr, int fq, const float (&rsv)[8]) const {
;         const int row0 = u.pm * BM + wr * 64 + fr, col0 = u.pn * HALF + wc * 32 + 8 * fq;
; #pragma unroll
;         for (int ai = 0; ai < 2; ++ai)
; #pragma unroll
;             for (int m = 0; m < 4; ++m) { bf16_t* rowp = O + (size_t)(row0 + ai * HALF + m * 16) * ldc + col0; float r[8]; const float rr = rsv[ai * 4 + m];
; #pragma unroll
;                 for (int n = 0; n < 2; ++n)
; #pragma unroll
;                     for (int j = 0; j < 4; ++j) { const float g = acc[ai][0][m][n][j] * rr, up = acc[ai][1][m][n][j] * rr;
;                         const float e = __builtin_amdgcn_exp2f(g * -1.4426950408889634f); r[n * 4 + j] = g * __builtin_amdgcn_rcpf(1.0f + e) * up; }
;                 u32x4 w; w.x = cvt_pk_bf16(r[0], r[1]); w.y = cvt_pk_bf16(r[2], r[3]); w.z = cvt_pk_bf16(r[4], r[5]); w.w = cvt_pk_bf16(r[6], r[7]);
;                 *(u32x4*)rowp = w; }
	v_mul_f32_e32 v175, 0xbfb8aa3b, v89
	v_exp_f32_e32 v168, v168
	v_exp_f32_e32 v169, v169
	v_exp_f32_e32 v170, v170
	v_exp_f32_e32 v171, v171
	v_exp_f32_e32 v172, v172
	v_exp_f32_e32 v173, v173
	v_exp_f32_e32 v174, v174
	v_exp_f32_e32 v175, v175
	v_add_f32_e32 v168, 1.0, v168
	v_add_f32_e32 v169, 1.0, v169
	v_add_f32_e32 v170, 1.0, v170
	v_add_f32_e32 v171, 1.0, v171
	v_add_f32_e32 v172, 1.0, v172
	v_add_f32_e32 v173, 1.0, v173
	v_add_f32_e32 v174, 1.0, v174
	v_add_f32_e32 v175, 1.0, v175
	v_rcp_f32_e32 v168, v168
	v_rcp_f32_e32 v169, v169
	v_rcp_f32_e32 v170, v170
	v_rcp_f32_e32 v171, v171
	v_rcp_f32_e32 v172, v172
	v_rcp_f32_e32 v173, v173
	v_rcp_f32_e32 v174, v174
	v_rcp_f32_e32 v175, v175
	v_mul_f32_e32 v94, v94, v168
	v_mul_f32_e32 v95, v95, v169
	v_mul_f32_e32 v96, v96, v170
	v_mul_f32_e32 v97, v97, v171
	v_mul_f32_e32 v86, v86, v172
	v_mul_f32_e32 v87, v87, v173
	v_mul_f32_e32 v88, v88, v174
	v_mul_f32_e32 v89, v89, v175
	v_mul_f32_e32 v94, v94, v90
	v_mul_f32_e32 v95, v95, v91
	v_mul_f32_e32 v96, v96, v92
	v_mul_f32_e32 v97, v97, v93
	v_mul_f32_e32 v86, v86, v82
	v_mul_f32_e32 v87, v87, v83
	v_mul_f32_e32 v88, v88, v84
	v_mul_f32_e32 v89, v89, v85
	v_lshl_add_u64 v[162:163], v[162:163], 0, v[164:165]
	v_cvt_pk_bf16_f32 v90, v94, v95
	v_cvt_pk_bf16_f32 v91, v96, v97
	v_cvt_pk_bf16_f32 v92, v86, v87
	v_cvt_pk_bf16_f32 v93, v88, v89
	global_store_dwordx4 v[162:163], v[90:93], off
	v_add_u32_e32 v176, 0x30, v142
	v_mad_i64_i32 v[166:167], s[42:43], v176, s65, v[154:155]
	v_mul_f32_e32 v78, v150, v78
	v_mul_f32_e32 v79, v150, v79
	v_mul_f32_e32 v80, v150, v80
	v_mul_f32_e32 v81, v150, v81
	v_mul_f32_e32 v70, v150, v70
	v_mul_f32_e32 v71, v150, v71
	v_mul_f32_e32 v72, v150, v72
	v_mul_f32_e32 v73, v150, v73
	v_mul_f32_e32 v74, v150, v74
	v_mul_f32_e32 v75, v150, v75
	v_mul_f32_e32 v76, v150, v76
	v_mul_f32_e32 v77, v150, v77
	v_mul_f32_e32 v66, v150, v66
	v_mul_f32_e32 v67, v150, v67
	v_mul_f32_e32 v68, v150, v68
	v_mul_f32_e32 v69, v150, v69
	v_mul_f32_e32 v168, 0xbfb8aa3b, v78
	v_mul_f32_e32 v169, 0xbfb8aa3b, v79
	v_mul_f32_e32 v170, 0xbfb8aa3b, v80
	v_mul_f32_e32 v171, 0xbfb8aa3b, v81
	v_mul_f32_e32 v172, 0xbfb8aa3b, v70
	v_mul_f32_e32 v173, 0xbfb8aa3b, v71
	v_mul_f32_e32 v174, 0xbfb8aa3b, v72
	v_mul_f32_e32 v175, 0xbfb8aa3b, v73
	v_exp_f32_e32 v168, v168
	v_exp_f32_e32 v169, v169
	v_exp_f32_e32 v170, v170
	v_exp_f32_e32 v171, v171
	v_exp_f32_e32 v172, v172
	v_exp_f32_e32 v173, v173
	v_exp_f32_e32 v174, v174
	v_exp_f32_e32 v175, v175
	v_add_f32_e32 v168, 1.0, v168
	v_add_f32_e32 v169, 1.0, v169
	v_add_f32_e32 v170, 1.0, v170
	v_add_f32_e32 v171, 1.0, v171
	v_add_f32_e32 v172, 1.0, v172
	v_add_f32_e32 v173, 1.0, v173
	v_add_f32_e32 v174, 1.0, v174
	v_add_f32_e32 v175, 1.0, v175
	v_rcp_f32_e32 v168, v168
	v_rcp_f32_e32 v169, v169
	v_rcp_f32_e32 v170, v170
	v_rcp_f32_e32 v171, v171
	v_rcp_f32_e32 v172, v172
	v_rcp_f32_e32 v173, v173
	v_rcp_f32_e32 v174, v174
	v_rcp_f32_e32 v175, v175
	v_mul_f32_e32 v78, v78, v168
	v_mul_f32_e32 v79, v79, v169
	v_mul_f32_e32 v80, v80, v170
	v_mul_f32_e32 v81, v81, v171
	v_mul_f32_e32 v70, v70, v172
	v_mul_f32_e32 v71, v71, v173
	v_mul_f32_e32 v72, v72, v174
	v_mul_f32_e32 v73, v73, v175
	v_mul_f32_e32 v78, v78, v74
	v_mul_f32_e32 v79, v79, v75
	v_mul_f32_e32 v80, v80, v76
	v_mul_f32_e32 v81, v81, v77
	v_mul_f32_e32 v70, v70, v66
	v_mul_f32_e32 v71, v71, v67
	v_mul_f32_e32 v72, v72, v68
	v_mul_f32_e32 v73, v73, v69
	v_lshl_add_u64 v[166:167], v[166:167], 0, v[164:165]
	v_cvt_pk_bf16_f32 v74, v78, v79
	v_cvt_pk_bf16_f32 v75, v80, v81
	v_cvt_pk_bf16_f32 v76, v70, v71
	v_cvt_pk_bf16_f32 v77, v72, v73
	global_store_dwordx4 v[166:167], v[74:77], off
	v_add_u32_e32 v176, 0x80, v142
	v_mad_i64_i32 v[162:163], s[42:43], v176, s65, v[154:155]
	v_mul_f32_e32 v62, v148, v62
	v_mul_f32_e32 v63, v148, v63
	v_mul_f32_e32 v64, v148, v64
	v_mul_f32_e32 v65, v148, v65
	v_mul_f32_e32 v54, v148, v54
	v_mul_f32_e32 v55, v148, v55
	v_mul_f32_e32 v56, v148, v56
	v_mul_f32_e32 v57, v148, v57
	v_mul_f32_e32 v58, v148, v58
	v_mul_f32_e32 v59, v148, v59
	v_mul_f32_e32 v60, v148, v60
	v_mul_f32_e32 v61, v148, v61
	v_mul_f32_e32 v50, v148, v50
	v_mul_f32_e32 v51, v148, v51
	v_mul_f32_e32 v52, v148, v52
	v_mul_f32_e32 v53, v148, v53
	v_mul_f32_e32 v168, 0xbfb8aa3b, v62
	v_mul_f32_e32 v169, 0xbfb8aa3b, v63
	v_mul_f32_e32 v170, 0xbfb8aa3b, v64
	v_mul_f32_e32 v171, 0xbfb8aa3b, v65
	v_mul_f32_e32 v172, 0xbfb8aa3b, v54
	v_mul_f32_e32 v173, 0xbfb8aa3b, v55
	v_mul_f32_e32 v174, 0xbfb8aa3b, v56
	v_mul_f32_e32 v175, 0xbfb8aa3b, v57
	v_exp_f32_e32 v168, v168
	v_exp_f32_e32 v169, v169
	v_exp_f32_e32 v170, v170
	v_exp_f32_e32 v171, v171
	v_exp_f32_e32 v172, v172
	v_exp_f32_e32 v173, v173
	v_exp_f32_e32 v174, v174
	v_exp_f32_e32 v175, v175
	v_add_f32_e32 v168, 1.0, v168
	v_add_f32_e32 v169, 1.0, v169
	v_add_f32_e32 v170, 1.0, v170
	v_add_f32_e32 v171, 1.0, v171
	v_add_f32_e32 v172, 1.0, v172
	v_add_f32_e32 v173, 1.0, v173
	v_add_f32_e32 v174, 1.0, v174
	v_add_f32_e32 v175, 1.0, v175
	v_rcp_f32_e32 v168, v168
	v_rcp_f32_e32 v169, v169
	v_rcp_f32_e32 v170, v170
	v_rcp_f32_e32 v171, v171
	v_rcp_f32_e32 v172, v172
	v_rcp_f32_e32 v173, v173
	v_rcp_f32_e32 v174, v174
	v_rcp_f32_e32 v175, v175
	v_mul_f32_e32 v62, v62, v168
	v_mul_f32_e32 v63, v63, v169
	v_mul_f32_e32 v64, v64, v170
	v_mul_f32_e32 v65, v65, v171
	v_mul_f32_e32 v54, v54, v172
	v_mul_f32_e32 v55, v55, v173
	v_mul_f32_e32 v56, v56, v174
	v_mul_f32_e32 v57, v57, v175
	v_mul_f32_e32 v62, v62, v58
	v_mul_f32_e32 v63, v63, v59
	v_mul_f32_e32 v64, v64, v60
	v_mul_f32_e32 v65, v65, v61
	v_mul_f32_e32 v54, v54, v50
	v_mul_f32_e32 v55, v55, v51
	v_mul_f32_e32 v56, v56, v52
	v_mul_f32_e32 v57, v57, v53
; __device__ __forceinline__ unsigned cvt_pk_bf16(float lo, float hi) { unsigned r; asm volatile("v_cvt_pk_bf16_f32 %0, %1, %2" : "=v"(r) : "v"(lo), "v"(hi)); return r; }
;     __device__ __forceinline__ void operator()(const f32x4 (&acc)[2][2][4][2], const Unit& u, int wr, int wc, int fr, int fq, const float (&rsv)[8]) const {
;         const int row0 = u.pm * BM + wr * 64 + fr, col0 = u.pn * HALF + wc * 32 + 8 * fq;
; #pragma unroll
;         for (int ai = 0; ai < 2; ++ai)
; #pragma unroll
;             for (int m = 0; m < 4; ++m) { bf16_t* rowp = O + (size_t)(row0 + ai * HALF + m * 16) * ldc + col0; float r[8]; const float rr = rsv[ai * 4 + m];
; #pragma unroll
;                 for (int n = 0; n < 2; ++n)
; #pragma unroll
;                     for (int j = 0; j < 4; ++j) { const float g = acc[ai][0][m][n][j] * rr, up = acc[ai][1][m][n][j] * rr;
;                         const float e = __builtin_amdgcn_exp2f(g * -1.4426950408889634f); r[n * 4 + j] = g * __builtin_amdgcn_rcpf(1.0f + e) * up; }
;                 u32x4 w; w.x = cvt_pk_bf16(r[0], r[1]); w.y = cvt_pk_bf16(r[2], r[3]); w.z = cvt_pk_bf16(r[4], r[5]); w.w = cvt_pk_bf16(r[6], r[7]);
;                 *(u32x4*)rowp = w; }
; template <class Epi, class Sched, bool ALIGN_EPI = false, bool SP2 = false>
; __device__ __forceinline__ void gemm_phase(PG8_LAS unsigned char* lds, const Gemm g, const Sched& S, const Epi& E, const int tid_in) {
;     ...
;         if constexpr (!Epi::AFTER_DRAIN) { E(acc, cur, wr, wc, fr, fq, rsv); S.done(cur); }
;         if (!has_next) break;
	v_lshl_add_u64 v[162:163], v[162:163], 0, v[164:165]
	v_cvt_pk_bf16_f32 v58, v62, v63
	v_cvt_pk_bf16_f32 v59, v64, v65
	v_cvt_pk_bf16_f32 v60, v54, v55
	v_cvt_pk_bf16_f32 v61, v56, v57
	global_store_dwordx4 v[162:163], v[58:61], off
	v_add_u32_e32 v176, 0x90, v142
	v_mad_i64_i32 v[166:167], s[42:43], v176, s65, v[154:155]
	v_mul_f32_e32 v46, v146, v46
	v_mul_f32_e32 v47, v146, v47
	v_mul_f32_e32 v48, v146, v48
	v_mul_f32_e32 v49, v146, v49
	v_mul_f32_e32 v38, v146, v38
	v_mul_f32_e32 v39, v146, v39
	v_mul_f32_e32 v40, v146, v40
	v_mul_f32_e32 v41, v146, v41
	v_mul_f32_e32 v42, v146, v42
	v_mul_f32_e32 v43, v146, v43
	v_mul_f32_e32 v44, v146, v44
	v_mul_f32_e32 v45, v146, v45
	v_mul_f32_e32 v34, v146, v34
	v_mul_f32_e32 v35, v146, v35
	v_mul_f32_e32 v36, v146, v36
	v_mul_f32_e32 v37, v146, v37
	v_mul_f32_e32 v168, 0xbfb8aa3b, v46
	v_mul_f32_e32 v169, 0xbfb8aa3b, v47
	v_mul_f32_e32 v170, 0xbfb8aa3b, v48
	v_mul_f32_e32 v171, 0xbfb8aa3b, v49
	v_mul_f32_e32 v172, 0xbfb8aa3b, v38
	v_mul_f32_e32 v173, 0xbfb8aa3b, v39
	v_mul_f32_e32 v174, 0xbfb8aa3b, v40
	v_mul_f32_e32 v175, 0xbfb8aa3b, v41
	v_exp_f32_e32 v168, v168
	v_exp_f32_e32 v169, v169
	v_exp_f32_e32 v170, v170
	v_exp_f32_e32 v171, v171
	v_exp_f32_e32 v172, v172
	v_exp_f32_e32 v173, v173
	v_exp_f32_e32 v174, v174
	v_exp_f32_e32 v175, v175
	v_add_f32_e32 v168, 1.0, v168
	v_add_f32_e32 v169, 1.0, v169
	v_add_f32_e32 v170, 1.0, v170
	v_add_f32_e32 v171, 1.0, v171
	v_add_f32_e32 v172, 1.0, v172
	v_add_f32_e32 v173, 1.0, v173
	v_add_f32_e32 v174, 1.0, v174
	v_add_f32_e32 v175, 1.0, v175
	v_rcp_f32_e32 v168, v168
	v_rcp_f32_e32 v169, v169
	v_rcp_f32_e32 v170, v170
	v_rcp_f32_e32 v171, v171
	v_rcp_f32_e32 v172, v172
	v_rcp_f32_e32 v173, v173
	v_rcp_f32_e32 v174, v174
	v_rcp_f32_e32 v175, v175
	v_mul_f32_e32 v46, v46, v168
	v_mul_f32_e32 v47, v47, v169
	v_mul_f32_e32 v48, v48, v170
	v_mul_f32_e32 v49, v49, v171
	v_mul_f32_e32 v38, v38, v172
	v_mul_f32_e32 v39, v39, v173
	v_mul_f32_e32 v40, v40, v174
	v_mul_f32_e32 v41, v41, v175
	v_mul_f32_e32 v46, v46, v42
	v_mul_f32_e32 v47, v47, v43
	v_mul_f32_e32 v48, v48, v44
	v_mul_f32_e32 v49, v49, v45
	v_mul_f32_e32 v38, v38, v34
	v_mul_f32_e32 v39, v39, v35
	v_mul_f32_e32 v40, v40, v36
	v_mul_f32_e32 v41, v41, v37
	v_lshl_add_u64 v[166:167], v[166:167], 0, v[164:165]
	v_cvt_pk_bf16_f32 v42, v46, v47
	v_cvt_pk_bf16_f32 v43, v48, v49
	v_cvt_pk_bf16_f32 v44, v38, v39
	v_cvt_pk_bf16_f32 v45, v40, v41
	global_store_dwordx4 v[166:167], v[42:45], off
	v_add_u32_e32 v176, 0xa0, v142
	v_mad_i64_i32 v[162:163], s[42:43], v176, s65, v[154:155]
	v_mul_f32_e32 v30, v144, v30
	v_mul_f32_e32 v31, v144, v31
	v_mul_f32_e32 v32, v144, v32
	v_mul_f32_e32 v33, v144, v33
	v_mul_f32_e32 v22, v144, v22
	v_mul_f32_e32 v23, v144, v23
	v_mul_f32_e32 v24, v144, v24
	v_mul_f32_e32 v25, v144, v25
	v_mul_f32_e32 v26, v144, v26
	v_mul_f32_e32 v27, v144, v27
	v_mul_f32_e32 v28, v144, v28
	v_mul_f32_e32 v29, v144, v29
	v_mul_f32_e32 v18, v144, v18
	v_mul_f32_e32 v19, v144, v19
	v_mul_f32_e32 v20, v144, v20
	v_mul_f32_e32 v21, v144, v21
	v_mul_f32_e32 v168, 0xbfb8aa3b, v30
	v_mul_f32_e32 v169, 0xbfb8aa3b, v31
	v_mul_f32_e32 v170, 0xbfb8aa3b, v32
	v_mul_f32_e32 v171, 0xbfb8aa3b, v33
	v_mul_f32_e32 v172, 0xbfb8aa3b, v22
	v_mul_f32_e32 v173, 0xbfb8aa3b, v23
	v_mul_f32_e32 v174, 0xbfb8aa3b, v24
	v_mul_f32_e32 v175, 0xbfb8aa3b, v25
	v_exp_f32_e32 v168, v168
	v_exp_f32_e32 v169, v169
	v_exp_f32_e32 v170, v170
	v_exp_f32_e32 v171, v171
	v_exp_f32_e32 v172, v172
	v_exp_f32_e32 v173, v173
	v_exp_f32_e32 v174, v174
	v_exp_f32_e32 v175, v175
	v_add_f32_e32 v168, 1.0, v168
	v_add_f32_e32 v169, 1.0, v169
	v_add_f32_e32 v170, 1.0, v170
	v_add_f32_e32 v171, 1.0, v171
	v_add_f32_e32 v172, 1.0, v172
	v_add_f32_e32 v173, 1.0, v173
	v_add_f32_e32 v174, 1.0, v174
	v_add_f32_e32 v175, 1.0, v175
	v_rcp_f32_e32 v168, v168
	v_rcp_f32_e32 v169, v169
	v_rcp_f32_e32 v170, v170
	v_rcp_f32_e32 v171, v171
	v_rcp_f32_e32 v172, v172
	v_rcp_f32_e32 v173, v173
	v_rcp_f32_e32 v174, v174
	v_rcp_f32_e32 v175, v175
	v_mul_f32_e32 v30, v30, v168
	v_mul_f32_e32 v31, v31, v169
	v_mul_f32_e32 v32, v32, v170
	v_mul_f32_e32 v33, v33, v171
	v_mul_f32_e32 v22, v22, v172
	v_mul_f32_e32 v23, v23, v173
	v_mul_f32_e32 v24, v24, v174
	v_mul_f32_e32 v25, v25, v175
	v_mul_f32_e32 v30, v30, v26
	v_mul_f32_e32 v31, v31, v27
	v_mul_f32_e32 v32, v32, v28
	v_mul_f32_e32 v33, v33, v29
	v_mul_f32_e32 v22, v22, v18
	v_mul_f32_e32 v23, v23, v19
	v_mul_f32_e32 v24, v24, v20
	v_mul_f32_e32 v25, v25, v21
	v_lshl_add_u64 v[162:163], v[162:163], 0, v[164:165]
	v_cvt_pk_bf16_f32 v26, v30, v31
	v_cvt_pk_bf16_f32 v27, v32, v33
	v_cvt_pk_bf16_f32 v28, v22, v23
	v_cvt_pk_bf16_f32 v29, v24, v25
	global_store_dwordx4 v[162:163], v[26:29], off
	v_add_u32_e32 v176, 0xb0, v142
	v_mad_i64_i32 v[166:167], s[42:43], v176, s65, v[154:155]
	v_mul_f32_e32 v14, v140, v14
	v_mul_f32_e32 v15, v140, v15
	v_mul_f32_e32 v16, v140, v16
	v_mul_f32_e32 v17, v140, v17
	v_mul_f32_e32 v6, v140, v6
	v_mul_f32_e32 v7, v140, v7
	v_mul_f32_e32 v8, v140, v8
	v_mul_f32_e32 v9, v140, v9
	v_mul_f32_e32 v10, v140, v10
	v_mul_f32_e32 v11, v140, v11
	v_mul_f32_e32 v12, v140, v12
	v_mul_f32_e32 v13, v140, v13
	v_mul_f32_e32 v2, v140, v2
	v_mul_f32_e32 v3, v140, v3
	v_mul_f32_e32 v4, v140, v4
	v_mul_f32_e32 v5, v140, v5
	v_mul_f32_e32 v168, 0xbfb8aa3b, v14
	v_mul_f32_e32 v169, 0xbfb8aa3b, v15
	v_mul_f32_e32 v170, 0xbfb8aa3b, v16
	v_mul_f32_e32 v171, 0xbfb8aa3b, v17
	v_mul_f32_e32 v172, 0xbfb8aa3b, v6
	v_mul_f32_e32 v173, 0xbfb8aa3b, v7
	v_mul_f32_e32 v174, 0xbfb8aa3b, v8
	v_mul_f32_e32 v175, 0xbfb8aa3b, v9
	v_exp_f32_e32 v168, v168
	v_exp_f32_e32 v169, v169
	v_exp_f32_e32 v170, v170
	v_exp_f32_e32 v171, v171
	v_exp_f32_e32 v172, v172
	v_exp_f32_e32 v173, v173
	v_exp_f32_e32 v174, v174
	v_exp_f32_e32 v175, v175
	v_add_f32_e32 v168, 1.0, v168
	v_add_f32_e32 v169, 1.0, v169
	v_add_f32_e32 v170, 1.0, v170
	v_add_f32_e32 v171, 1.0, v171
	v_add_f32_e32 v172, 1.0, v172
	v_add_f32_e32 v173, 1.0, v173
	v_add_f32_e32 v174, 1.0, v174
	v_add_f32_e32 v175, 1.0, v175
	v_rcp_f32_e32 v168, v168
	v_rcp_f32_e32 v169, v169
	v_rcp_f32_e32 v170, v170
	v_rcp_f32_e32 v171, v171
	v_rcp_f32_e32 v172, v172
	v_rcp_f32_e32 v173, v173
	v_rcp_f32_e32 v174, v174
	v_rcp_f32_e32 v175, v175
	v_mul_f32_e32 v14, v14, v168
	v_mul_f32_e32 v15, v15, v169
	v_mul_f32_e32 v16, v16, v170
	v_mul_f32_e32 v17, v17, v171
	v_mul_f32_e32 v6, v6, v172
	v_mul_f32_e32 v7, v7, v173
	v_mul_f32_e32 v8, v8, v174
	v_mul_f32_e32 v9, v9, v175
	v_mul_f32_e32 v14, v14, v10
	v_mul_f32_e32 v15, v15, v11
	v_mul_f32_e32 v16, v16, v12
	v_mul_f32_e32 v17, v17, v13
	v_mul_f32_e32 v6, v6, v2
	v_mul_f32_e32 v7, v7, v3
	v_mul_f32_e32 v8, v8, v4
	v_mul_f32_e32 v9, v9, v5
	v_lshl_add_u64 v[166:167], v[166:167], 0, v[164:165]
	v_cvt_pk_bf16_f32 v10, v14, v15
	v_cvt_pk_bf16_f32 v11, v16, v17
	v_cvt_pk_bf16_f32 v12, v6, v7
	v_cvt_pk_bf16_f32 v13, v8, v9
	global_store_dwordx4 v[166:167], v[10:13], off
	s_mov_b64 s[70:71], -1
	s_andn2_b64 vcc, exec, s[4:5]
	s_cbranch_vccnz .LBB0_618
; #define PG8_BAR __builtin_amdgcn_s_barrier()
; template <class Epi, class Sched, bool ALIGN_EPI = false, bool SP2 = false>
; __device__ __forceinline__ void gemm_phase(PG8_LAS unsigned char* lds, const Gemm g, const Sched& S, const Epi& E, const int tid_in) {
;     ...
;         cur = nxt; cA = nA; cB = nB; ++ui;
;         if constexpr (ALIGN_EPI) { if (wr == 1) PG8_BAR; }
;     }
	s_andn2_b64 vcc, exec, s[10:11]
	s_cbranch_vccnz .LBB0_617
	s_barrier
	s_branch .LBB0_617
